# P16: GEMM steps wait for grid-barrier completion right before the first prologue load (per-step address set-up now overlaps the barrier); unit-less workgroups wait on their own path
# speedup vs baseline: 1.0141x; 1.0042x over previous
; __device__ __forceinline__ unsigned xb_ld(unsigned* p)              { return __hip_atomic_load(p, __ATOMIC_RELAXED, __HIP_MEMORY_SCOPE_AGENT); }
; #define XB_SPIN(cond, bar) do { unsigned _sp = 0; while (cond) { __builtin_amdgcn_s_sleep(1); \
;     if ((++_sp & 255u) == 0u) { if (xb_ld(&(bar)[XB_TMO])) break; if (_sp > XB_SPIN_CAP) { atomicAdd(&(bar)[XB_TMO], 1u); break; } } } } while (0)
; #define PG8_STAGE(bufoff, gbase, voff) do { _Pragma("unroll") for (int _i = 0; _i < 2; ++_i) { unsigned _vo = (voff)[_i]; asm volatile("" : "+v"(_vo));   \
;         __builtin_amdgcn_global_load_lds((const unsigned*)((const char*)(gbase) + _vo), (LAS unsigned*)(lds + (bufoff) + ldsw + _i * 8192), 16, 0, 0); } } while (0)
; __device__ __forceinline__ void xcd_barrier(const XcdBarrier& b) {
;     ...
;         XB_SPIN((int)(xb_ld(&bar[XB_TOP]) - target) < 0, bar);
; __device__ __forceinline__ void gemm_phase(LAS unsigned char* lds, const Call& C, const int tid, const Args& args) {
;     ...
;     for (int i = 0; i < 2; ++i) { int R, Cc; stage_rc(tid * 16 + i * 8192, R, Cc); const int Rb = (R & ~31) + perm32(R & 31);
;         voffA[i] = (unsigned)(R * C.lda + Cc) * 2u; voffB[i] = (unsigned)(Rb * C.ldb + Cc) * 2u; }
;     const size_t kstep = (size_t)(BK * 2);
;     const size_t hstepA = (size_t)HALF * C.lda * 2, hstepB = (size_t)HALF * C.ldb * 2;
;     const unsigned ldsw = (unsigned)wid * 1024u;
;     const int aoff = lds_byte(wr * 64 + fr, fq * 8), boff = lds_byte(wc * 32 + fr, fq * 8);
;     ...
;     Unit cur, nxt; int ui = 0;
;     next_unit(C, 0, cur.pm, cur.pn, cur.kp0, cur.np, cur.slice);
;     if (cur.pm < 0) return;
;     f32x4 acc[2][2][4][2];
; #pragma unroll
;     for (int a = 0; a < 2; ++a)
; #pragma unroll
;         for (int b = 0; b < 2; ++b)
; #pragma unroll
;             for (int m = 0; m < 4; ++m)
; #pragma unroll
;                 for (int n = 0; n < 2; ++n) acc[a][b][m][n] = (f32x4){0.f, 0.f, 0.f, 0.f};
;     bf16x8 At[4][2], B0[2][2], B1[2][2];
;     const char* cA = PG8_APTR(cur); const char* cB = PG8_BPTR(cur);
;     PG8_STAGE(PG8_SB(0, 0), cB, voffB); PG8_STAGE(PG8_SB(0, 1), cB + hstepB, voffB); PG8_STAGE(PG8_SA(0, 0), cA, voffA); PG8_STAGE(PG8_SA(0, 1), cA + hstepA, voffA);
.LBB0_261:
	v_readlane_b32 s24, v254, 19
	v_readlane_b32 s48, v254, 17
	s_cmp_lt_i32 s90, 0
	v_lshlrev_b32_e32 v85, 4, v204
	v_readlane_b32 s4, v254, 11
	v_readlane_b32 s25, v254, 20
	v_readlane_b32 s42, v254, 31
	v_readlane_b32 s44, v254, 39
	v_readlane_b32 s49, v254, 18
	s_cbranch_scc1 .Lp16_nounit
	v_ashrrev_i32_e32 v1, 31, v85
	v_lshrrev_b32_e32 v1, 22, v1
	v_add_u32_e32 v1, v85, v1
	v_and_b32_e32 v1, 0xfffffc00, v1
	v_sub_u32_e32 v1, v85, v1
	v_ashrrev_i32_e32 v0, 31, v204
	v_lshrrev_b32_e32 v2, 4, v1
	v_lshrrev_b32_e32 v0, 26, v0
	v_bitop3_b32 v2, v2, v1, 32 bitop3:0x6c
	v_ashrrev_i32_e32 v1, 31, v1
	v_add_u32_e32 v0, v204, v0
	v_lshrrev_b32_e32 v1, 26, v1
	v_ashrrev_i32_e32 v0, 6, v0
	v_add_u32_e32 v1, v2, v1
	v_lshlrev_b32_e32 v3, 3, v0
	v_ashrrev_i32_e32 v4, 6, v1
	v_and_b32_e32 v1, 0xc0, v1
	v_and_b32_e32 v3, -16, v3
	v_lshlrev_b32_e32 v0, 5, v0
	v_sub_u32_e32 v1, v2, v1
	v_add_u32_e32 v3, v4, v3
	v_and_b32_e32 v0, 32, v0
	v_ashrrev_i16_sdwa v1, v226, sext(v1) dst_sel:DWORD dst_unused:UNUSED_PAD src0_sel:DWORD src1_sel:BYTE_0
	v_add_u32_sdwa v0, v0, sext(v1) dst_sel:DWORD dst_unused:UNUSED_PAD src0_sel:DWORD src1_sel:WORD_0
	v_lshlrev_b32_e32 v1, 1, v3
	v_lshrrev_b32_e32 v2, 2, v3
	v_and_b32_e32 v4, 3, v4
	s_mov_b32 s4, 0x7fffffe0
	v_and_b32_e32 v1, 24, v1
	v_and_b32_e32 v2, 4, v2
	v_and_or_b32 v4, v3, s4, v4
	v_or3_b32 v1, v4, v2, v1
	v_mul_lo_u32 v2, s52, v3
	v_mul_lo_u32 v1, s52, v1
	v_add_lshl_u32 v205, v2, v0, 1
	v_add_lshl_u32 v242, v1, v0, 1
	v_add_u32_e32 v0, 0x2000, v85
	v_ashrrev_i32_e32 v1, 31, v0
	v_lshrrev_b32_e32 v1, 22, v1
	v_add_u32_e32 v1, v0, v1
	v_ashrrev_i32_e32 v1, 10, v1
	v_mul_i32_i24_e32 v2, 0x400, v1
	v_sub_u32_e32 v0, v0, v2
	v_lshrrev_b32_e32 v2, 4, v0
	v_bitop3_b32 v0, v2, v0, 32 bitop3:0x6c
	v_ashrrev_i32_e32 v3, 31, v0
	v_writelane_b32 v254, s51, 52
	v_lshrrev_b32_e32 v3, 26, v3
	v_writelane_b32 v254, s88, 53
	v_lshlrev_b32_e32 v2, 3, v1
	v_add_u32_e32 v3, v0, v3
	v_writelane_b32 v254, s89, 54
	v_and_b32_e32 v2, -16, v2
	v_ashrrev_i32_e32 v4, 6, v3
	v_writelane_b32 v254, s90, 55
	v_add_u32_e32 v2, v4, v2
	v_and_b32_e32 v4, 3, v4
	v_writelane_b32 v254, s91, 56
	s_ashr_i32 s12, s5, 6
	v_and_or_b32 v4, v2, s4, v4
	s_lshl_b32 s22, s52, 8
	s_mov_b32 s53, s29
	s_lshl_b32 s4, s90, 1
	s_ashr_i32 s13, s5, 8
	s_lshl_b64 s[74:75], s[52:53], 8
	s_lshl_b32 s23, s12, 10
	s_mul_hi_u32 s8, s4, s22
	s_mul_i32 s4, s4, s22
	v_readlane_b32 s34, v254, 25
	v_readlane_b32 s35, v254, 26
	s_add_u32 s4, s34, s4
	s_addc_u32 s14, s35, s8
	s_ashr_i32 s8, s78, 31
	s_lshl_b64 s[76:77], s[52:53], 9
	v_and_b32_e32 v3, 0xc0, v3
	s_mul_i32 s8, s76, s8
	s_mul_hi_u32 s9, s76, s78
	v_lshlrev_b32_e32 v1, 5, v1
	v_sub_u32_e32 v0, v0, v3
	s_add_i32 s8, s9, s8
	s_lshr_b32 s9, s52, 23
	v_and_b32_e32 v1, 32, v1
	v_ashrrev_i16_sdwa v0, v226, sext(v0) dst_sel:DWORD dst_unused:UNUSED_PAD src0_sel:DWORD src1_sel:BYTE_0
	s_mul_i32 s9, s9, s78
	v_add_u32_sdwa v0, v1, sext(v0) dst_sel:DWORD dst_unused:UNUSED_PAD src0_sel:DWORD src1_sel:WORD_0
	v_lshlrev_b32_e32 v1, 1, v2
	v_lshrrev_b32_e32 v3, 2, v2
	s_add_i32 s8, s8, s9
	s_mul_i32 s9, s76, s78
	v_and_b32_e32 v1, 24, v1
	v_and_b32_e32 v3, 4, v3
	s_add_u32 s9, s24, s9
	v_or3_b32 v1, v4, v3, v1
	s_addc_u32 s17, s25, s8
	v_mul_lo_u32 v2, s52, v2
	v_mul_lo_u32 v1, s52, v1
	s_add_u32 s8, s9, s0
	v_add_lshl_u32 v243, v2, v0, 1
	v_add_lshl_u32 v244, v1, v0, 1
	s_addc_u32 s9, s17, s1
	s_cmp_eq_u32 s100, 0
	s_cbranch_scc1 .Lp16a_skip
	s_mov_b32 s100, 0
	v_readlane_b32 vcc_lo, v253, 35
	s_nop 3
	s_cmp_lg_u32 vcc_lo, 0
	s_cbranch_scc1 .Lp16a_all
	s_mov_b64 exec, 1
	s_waitcnt vmcnt(0)
	v_readfirstlane_b32 vcc_lo, v250
	s_sub_i32 vcc_lo, vcc_lo, s101
	s_cmp_lt_i32 vcc_lo, 0
	s_cbranch_scc0 .Lp16a_done
	v_readlane_b32 vcc_lo, v253, 24
	v_mov_b32_e32 v251, 0
	s_nop 1
	s_and_b32 vcc_lo, vcc_lo, 0x700
	v_mov_b32_e32 v250, vcc_lo
	v_add_u32_e32 v250, 0x3400, v250
	v_readlane_b32 vcc_lo, v253, 33
	v_readlane_b32 vcc_hi, v253, 34
	s_nop 1
	v_lshl_add_u64 v[248:249], vcc, 0, v[250:251]
	s_mov_b32 vcc_hi, 0

; #define PG8_STAGE(bufoff, gbase, voff) do { _Pragma("unroll") for (int _i = 0; _i < 2; ++_i) { unsigned _vo = (voff)[_i]; asm volatile("" : "+v"(_vo));   \
;         __builtin_amdgcn_global_load_lds((const unsigned*)((const char*)(gbase) + _vo), (LAS unsigned*)(lds + (bufoff) + ldsw + _i * 8192), 16, 0, 0); } } while (0)
; #define PG8_WAIT_V(n) asm volatile("s_waitcnt vmcnt(" #n ")" ::: "memory")
; #define PG8_BAR __builtin_amdgcn_s_barrier()
; __device__ __forceinline__ void gemm_phase(LAS unsigned char* lds, const Call& C, const int tid, const Args& args) {
;     ...
;     PG8_STAGE(PG8_SB(0, 0), cB, voffB); PG8_STAGE(PG8_SB(0, 1), cB + hstepB, voffB); PG8_STAGE(PG8_SA(0, 0), cA, voffA); PG8_STAGE(PG8_SA(0, 1), cA + hstepA, voffA);
;     if (wr == 1) PG8_BAR;
;     PG8_WAIT_V(2); PG8_BAR;
;     PG8_STAGE(PG8_SB(1, 0), cB + kstep, voffB); PG8_STAGE(PG8_SA(1, 0), cA + kstep, voffA); PG8_STAGE(PG8_SB(1, 1), cB + hstepB + kstep, voffB);
.Lp16a_skip:
	s_add_i32 s20, s23, 0
	v_mov_b32_e32 v0, v242
	s_add_i32 m0, s20, 0x10000
	s_nop 0
	global_load_lds_dwordx4 v0, s[8:9]
	v_mov_b32_e32 v0, v244
	s_add_i32 m0, s20, 0x12000
	s_add_u32 s34, s8, s74
	global_load_lds_dwordx4 v0, s[8:9]
	v_mov_b32_e32 v0, v242
	s_addc_u32 s35, s9, s75
	s_add_i32 m0, s20, 0x14000
	s_nop 0
	global_load_lds_dwordx4 v0, s[34:35]
	v_mov_b32_e32 v0, v244
	s_add_i32 m0, s20, 0x16000
	s_add_u32 s0, s4, s0
	global_load_lds_dwordx4 v0, s[34:35]
	v_mov_b32_e32 v0, v205
	s_addc_u32 s1, s14, s1
	s_mov_b32 m0, s20
	s_add_i32 s72, s20, 0x2000
	global_load_lds_dwordx4 v0, s[0:1]
	v_mov_b32_e32 v0, v243
	s_mov_b32 m0, s72
	s_add_u32 s24, s0, s22
	global_load_lds_dwordx4 v0, s[0:1]
	s_addc_u32 s25, s1, 0
	s_add_i32 s73, s20, 0x4000
	v_mov_b32_e32 v0, v205
	s_mov_b32 m0, s73
	s_add_i32 s4, s20, 0x6000
	global_load_lds_dwordx4 v0, s[24:25]
	v_mov_b32_e32 v0, v243
	s_mov_b32 m0, s4
	s_cmp_eq_u32 s13, 1
	global_load_lds_dwordx4 v0, s[24:25]
	s_cselect_b64 s[24:25], -1, 0
	v_writelane_b32 v254, s24, 57
	v_mov_b32_e32 v80, v242
	s_add_i32 m0, s20, 0x18000
	v_lshl_add_u64 v[0:1], s[8:9], 0, v[80:81]
	v_lshl_add_u64 v[0:1], v[0:1], 0, s[18:19]
	v_mov_b32_e32 v80, v244
	global_load_lds_dwordx4 v[0:1], off
	s_add_i32 m0, s20, 0x1a000
	v_lshl_add_u64 v[0:1], s[8:9], 0, v[80:81]
	v_lshl_add_u64 v[0:1], v[0:1], 0, s[18:19]
	v_mov_b32_e32 v80, v205
	global_load_lds_dwordx4 v[0:1], off
	s_add_i32 s14, s20, 0x8000
	v_lshl_add_u64 v[0:1], s[0:1], 0, v[80:81]
	v_lshl_add_u64 v[0:1], v[0:1], 0, s[18:19]
	s_mov_b32 m0, s14
	v_mov_b32_e32 v80, v243
	global_load_lds_dwordx4 v[0:1], off
	s_add_i32 s52, s20, 0xa000
	v_lshl_add_u64 v[0:1], s[0:1], 0, v[80:81]
	v_lshl_add_u64 v[0:1], v[0:1], 0, s[18:19]
	s_mov_b32 m0, s52
	v_mov_b32_e32 v80, v242
	s_nop 0
	global_load_lds_dwordx4 v[0:1], off
	v_lshl_add_u64 v[0:1], s[34:35], 0, v[80:81]
	s_add_i32 m0, s20, 0x1c000
	v_lshl_add_u64 v[0:1], v[0:1], 0, s[18:19]
	s_nop 0
	global_load_lds_dwordx4 v[0:1], off
	s_cmp_lg_u32 s13, 1
	s_nop 0
	v_writelane_b32 v254, s25, 58
	s_cbranch_scc1 .LBB0_264
	s_barrier

; __device__ __forceinline__ unsigned xb_ld(unsigned* p)              { return __hip_atomic_load(p, __ATOMIC_RELAXED, __HIP_MEMORY_SCOPE_AGENT); }
; #define XB_SPIN(cond, bar) do { unsigned _sp = 0; while (cond) { __builtin_amdgcn_s_sleep(1); \
;     if ((++_sp & 255u) == 0u) { if (xb_ld(&(bar)[XB_TMO])) break; if (_sp > XB_SPIN_CAP) { atomicAdd(&(bar)[XB_TMO], 1u); break; } } } } while (0)
; __device__ __forceinline__ void xcd_barrier(const XcdBarrier& b) {
;     ...
;         XB_SPIN((int)(xb_ld(&bar[XB_TOP]) - target) < 0, bar);
; __device__ __forceinline__ void gemm_phase(LAS unsigned char* lds, const Call& C, const int tid, const Args& args) {
;     ...
;     if (cur.pm < 0) return;
.LBB0_498:
	s_mov_b64 s[16:17], 0
	s_cbranch_execnz .LBB0_707
	s_branch .LBB0_770
.Lp16_nounit:
	s_cmp_eq_u32 s100, 0
	s_cbranch_scc1 .Lp16b_skip
	s_mov_b32 s100, 0
	v_readlane_b32 vcc_lo, v253, 35
	s_nop 3
	s_cmp_lg_u32 vcc_lo, 0
	s_cbranch_scc1 .Lp16b_all
	s_mov_b64 exec, 1
	s_waitcnt vmcnt(0)
	v_readfirstlane_b32 vcc_lo, v250
	s_sub_i32 vcc_lo, vcc_lo, s101
	s_cmp_lt_i32 vcc_lo, 0
	s_cbranch_scc0 .Lp16b_done
	v_readlane_b32 vcc_lo, v253, 24
	v_mov_b32_e32 v251, 0
	s_nop 1
	s_and_b32 vcc_lo, vcc_lo, 0x700
	v_mov_b32_e32 v250, vcc_lo
	v_add_u32_e32 v250, 0x3400, v250
	v_readlane_b32 vcc_lo, v253, 33
	v_readlane_b32 vcc_hi, v253, 34
	s_nop 1
	v_lshl_add_u64 v[248:249], vcc, 0, v[250:251]
	s_mov_b32 vcc_hi, 0

; __device__ __forceinline__ void gemm_phase(LAS unsigned char* lds, const Call& C, const int tid, const Args& args) {
;     ...
;     if (cur.pm < 0) return;
.Lp16b_all:
	s_waitcnt vmcnt(0) lgkmcnt(0)
	s_barrier
.Lp16b_skip:
	s_branch .LBB0_502
.LBB0_499:
	s_or_b64 exec, exec, s[0:1]
	s_cbranch_execz .LBB0_250
	s_branch .LBB0_772
